# P2b queue order: all unit classes sorted longest-first by modelled duration (diff qb15..6, then sb/diff interleaved by duration, memory units before the small ones); on top of v58
# baseline (speedup 1.0000x reference)
.LBB0_349:
	v_readlane_b32 s0, v255, 16
	s_waitcnt lgkmcnt(0)
	s_barrier
	v_mov_b32_e32 v0, s0
	ds_read_b32 v0, v0
	s_movk_i32 s0, 0x4ff
	s_waitcnt lgkmcnt(0)
	s_barrier
	v_cmp_lt_u32_e32 vcc, s0, v0
	v_readfirstlane_b32 s16, v0
	s_mov_b64 s[0:1], -1
	s_cbranch_vccnz .LBB0_342
	s_lshr_b32 s4, s16, 5
	s_lshr_b32 s5, s4, 2
	s_and_b32 s4, s4, 3
	s_lshl_b32 s4, s4, 3
	s_mov_b32 vcc_lo, 0x7050301
	s_cmp_eq_u32 s5, 1
	s_cselect_b32 vcc_lo, 0xf0d0b09, vcc_lo
	s_cmp_eq_u32 s5, 2
	s_cselect_b32 vcc_lo, 0x2001311, vcc_lo
	s_cmp_eq_u32 s5, 3
	s_cselect_b32 vcc_lo, 0x17060415, vcc_lo
	s_cmp_eq_u32 s5, 4
	s_cselect_b32 vcc_lo, 0xc190a08, vcc_lo
	s_cmp_eq_u32 s5, 5
	s_cselect_b32 vcc_lo, 0x121b100e, vcc_lo
	s_cmp_eq_u32 s5, 6
	s_cselect_b32 vcc_lo, 0x23222120, vcc_lo
	s_cmp_eq_u32 s5, 7
	s_cselect_b32 vcc_lo, 0x27262524, vcc_lo
	s_cmp_eq_u32 s5, 8
	s_cselect_b32 vcc_lo, 0x18161d14, vcc_lo
	s_cmp_eq_u32 s5, 9
	s_cselect_b32 vcc_lo, 0x1e1c1a1f, vcc_lo
	s_lshr_b32 vcc_lo, vcc_lo, s4
	s_and_b32 vcc_lo, vcc_lo, 0xff
	s_lshl_b32 vcc_lo, vcc_lo, 5
	s_and_b32 s16, s16, 31
	s_or_b32 s16, s16, vcc_lo
	s_cmpk_gt_u32 s16, 0x3ff
	s_cbranch_scc0 .LBB0_352
	v_readlane_b32 s0, v255, 55
	v_readlane_b32 s1, v255, 56
	v_readlane_b32 s4, v255, 22
	s_add_i32 s4, s4, 2
	s_mul_i32 s4, s4, s80
	v_mov_b32_e32 v0, 0
	s_mov_b32 s5, 0
	s_nop 3
